# FoX unit prologue: own-key row (4 x 16 B) and cumulative forget value loaded in one round trip instead of five dependent ones
# baseline (speedup 1.0000x reference)
.LBB0_751:
	s_or_b64 exec, exec, s[4:5]
	s_ashr_i32 s9, s8, 31
	s_lshl_b64 s[4:5], s[8:9], 15
	s_add_u32 s1, s30, s4
	s_addc_u32 s5, s31, s5
	s_add_u32 s4, s1, 0x100000
	s_addc_u32 s5, s5, 0
	s_ashr_i32 s1, s10, 1
	s_cmp_gt_i32 s1, 0
	s_cselect_b64 vcc, -1, 0
	s_cmp_gt_i32 s1, 1
	v_cndmask_b32_e32 v0, 0, v0, vcc
	s_cselect_b64 vcc, -1, 0
	s_cmp_gt_i32 s1, 2
	s_waitcnt vmcnt(0)
	v_cndmask_b32_e32 v10, 0, v11, vcc
	s_cselect_b64 vcc, -1, 0
	s_cmp_gt_i32 s1, 3
	v_add_f32_e32 v0, v10, v0
	v_cndmask_b32_e32 v10, 0, v12, vcc
	s_cselect_b64 vcc, -1, 0
	s_cmp_gt_i32 s1, 4
	v_add_f32_e32 v0, v10, v0
	v_cndmask_b32_e32 v10, 0, v13, vcc
	s_cselect_b64 vcc, -1, 0
	s_cmp_gt_i32 s1, 5
	v_add_f32_e32 v0, v10, v0
	v_cndmask_b32_e32 v6, 0, v6, vcc
	s_cselect_b64 vcc, -1, 0
	s_cmp_gt_i32 s1, 6
	v_add_f32_e32 v0, v6, v0
	v_cndmask_b32_e32 v6, 0, v7, vcc
	s_cselect_b64 vcc, -1, 0
	s_cmp_gt_i32 s1, 7
	v_add_f32_e32 v0, v6, v0
	v_cndmask_b32_e32 v6, 0, v8, vcc
	s_cselect_b64 vcc, -1, 0
	s_cmp_gt_i32 s1, 8
	v_add_f32_e32 v0, v6, v0
	v_cndmask_b32_e32 v6, 0, v9, vcc
	s_cselect_b64 vcc, -1, 0
	s_cmp_gt_i32 s1, 9
	v_add_f32_e32 v0, v6, v0
	v_cndmask_b32_e32 v2, 0, v2, vcc
	s_cselect_b64 vcc, -1, 0
	s_cmp_gt_i32 s1, 10
	v_add_f32_e32 v0, v2, v0
	v_cndmask_b32_e32 v2, 0, v3, vcc
	s_cselect_b64 vcc, -1, 0
	s_cmp_gt_i32 s1, 11
	v_add_f32_e32 v0, v2, v0
	v_cndmask_b32_e32 v2, 0, v4, vcc
	s_cselect_b64 vcc, -1, 0
	s_cmp_gt_i32 s1, 12
	v_add_f32_e32 v0, v2, v0
	v_cndmask_b32_e32 v2, 0, v5, vcc
	s_cselect_b64 vcc, -1, 0
	s_cmp_gt_i32 s1, 13
	v_add_f32_e32 v0, v2, v0
	v_cndmask_b32_e32 v2, 0, v14, vcc
	s_cselect_b64 vcc, -1, 0
	s_cmp_gt_i32 s1, 14
	v_add_f32_e32 v0, v2, v0
	v_cndmask_b32_e32 v2, 0, v15, vcc
	s_cselect_b64 vcc, -1, 0
	s_ashr_i32 s1, s0, 31
	s_lshl_b64 s[0:1], s[0:1], 2
	s_add_u32 s0, s4, s0
	s_addc_u32 s1, s5, s1
	global_load_dword v22, v1, s[0:1]
	global_load_dwordx4 v[4:7], v[18:19], off offset:1024
	global_load_dwordx4 v[224:227], v[18:19], off offset:1056
	global_load_dwordx4 v[228:231], v[18:19], off offset:1088
	global_load_dwordx4 v[232:235], v[18:19], off offset:1120
	v_ashrrev_i32_e32 v239, 31, v154
	v_mov_b32_e32 v238, v154
	v_lshl_add_u64 v[238:239], v[238:239], 2, s[4:5]
	global_load_dword v236, v[238:239], off
	v_add_f32_e32 v0, v2, v0
	v_cndmask_b32_e32 v2, 0, v16, vcc
	v_add_f32_e32 v0, v2, v0
	v_lshlrev_b32_e32 v2, 16, v116
	v_and_b32_e32 v8, 0xffff0000, v116
	v_and_b32_e32 v197, 64, v186
	s_mov_b32 s0, 0xf800000
	v_ashrrev_i32_e32 v155, 31, v154
	v_and_b32_e32 v21, 63, v159
	v_cmp_eq_u32_e64 s[6:7], 0, v21
	s_waitcnt vmcnt(0)
	v_lshlrev_b32_e32 v3, 16, v4
	v_fma_f32 v3, v2, v3, 0
	v_and_b32_e32 v9, 0xffff0000, v4
	v_mul_f32_e32 v4, v8, v8
	v_fmac_f32_e32 v4, v2, v2
	v_fmac_f32_e32 v3, v8, v9
	v_lshlrev_b32_e32 v2, 16, v117
	v_lshlrev_b32_e32 v8, 16, v5
	v_fmac_f32_e32 v4, v2, v2
	v_fmac_f32_e32 v3, v2, v8
	v_and_b32_e32 v2, 0xffff0000, v117
	v_and_b32_e32 v5, 0xffff0000, v5
	v_fmac_f32_e32 v4, v2, v2
	v_fmac_f32_e32 v3, v2, v5
	v_lshlrev_b32_e32 v2, 16, v118
	v_lshlrev_b32_e32 v5, 16, v6
	v_fmac_f32_e32 v4, v2, v2
	v_fmac_f32_e32 v3, v2, v5
	v_and_b32_e32 v2, 0xffff0000, v118
	v_and_b32_e32 v5, 0xffff0000, v6
	v_fmac_f32_e32 v4, v2, v2
	v_fmac_f32_e32 v3, v2, v5
	v_lshlrev_b32_e32 v2, 16, v119
	v_lshlrev_b32_e32 v5, 16, v7
	v_fmac_f32_e32 v3, v2, v5
	v_and_b32_e32 v5, 0xffff0000, v7
	v_fmac_f32_e32 v4, v2, v2
	v_and_b32_e32 v2, 0xffff0000, v119
	v_fmac_f32_e32 v4, v2, v2
	v_fmac_f32_e32 v3, v2, v5
	v_lshlrev_b32_e32 v2, 16, v120
	v_fmac_f32_e32 v4, v2, v2
	s_waitcnt vmcnt(0)
	v_lshlrev_b32_e32 v5, 16, v224
	v_fmac_f32_e32 v3, v2, v5
	v_and_b32_e32 v2, 0xffff0000, v120
	v_and_b32_e32 v5, 0xffff0000, v224
	v_fmac_f32_e32 v4, v2, v2
	v_fmac_f32_e32 v3, v2, v5
	v_lshlrev_b32_e32 v2, 16, v121
	v_lshlrev_b32_e32 v5, 16, v225
	v_fmac_f32_e32 v4, v2, v2
	v_fmac_f32_e32 v3, v2, v5
	v_and_b32_e32 v2, 0xffff0000, v121
	v_and_b32_e32 v5, 0xffff0000, v225
	v_fmac_f32_e32 v4, v2, v2
	v_fmac_f32_e32 v3, v2, v5
	v_lshlrev_b32_e32 v2, 16, v122
	v_lshlrev_b32_e32 v5, 16, v226
	v_fmac_f32_e32 v4, v2, v2
	v_fmac_f32_e32 v3, v2, v5
	v_and_b32_e32 v2, 0xffff0000, v122
	v_and_b32_e32 v5, 0xffff0000, v226
	v_fmac_f32_e32 v4, v2, v2
	v_fmac_f32_e32 v3, v2, v5
	v_lshlrev_b32_e32 v2, 16, v123
	v_lshlrev_b32_e32 v5, 16, v227
	v_fmac_f32_e32 v3, v2, v5
	v_and_b32_e32 v5, 0xffff0000, v227
	v_fmac_f32_e32 v4, v2, v2
	v_and_b32_e32 v2, 0xffff0000, v123
	v_fmac_f32_e32 v4, v2, v2
	v_fmac_f32_e32 v3, v2, v5
	v_lshlrev_b32_e32 v2, 16, v124
	v_fmac_f32_e32 v4, v2, v2
	s_waitcnt vmcnt(0)
	v_lshlrev_b32_e32 v5, 16, v228
	v_fmac_f32_e32 v3, v2, v5
	v_and_b32_e32 v2, 0xffff0000, v124
	v_and_b32_e32 v5, 0xffff0000, v228
	v_fmac_f32_e32 v4, v2, v2
	v_fmac_f32_e32 v3, v2, v5
	v_lshlrev_b32_e32 v2, 16, v125
	v_lshlrev_b32_e32 v5, 16, v229
	v_fmac_f32_e32 v4, v2, v2
	v_fmac_f32_e32 v3, v2, v5
	v_and_b32_e32 v2, 0xffff0000, v125
	v_and_b32_e32 v5, 0xffff0000, v229
	v_fmac_f32_e32 v4, v2, v2
	v_fmac_f32_e32 v3, v2, v5
	v_lshlrev_b32_e32 v2, 16, v126
	v_lshlrev_b32_e32 v5, 16, v230
	v_fmac_f32_e32 v4, v2, v2
	v_fmac_f32_e32 v3, v2, v5
	v_and_b32_e32 v2, 0xffff0000, v126
	v_and_b32_e32 v5, 0xffff0000, v230
	v_fmac_f32_e32 v4, v2, v2
	v_fmac_f32_e32 v3, v2, v5
	v_lshlrev_b32_e32 v2, 16, v127
	v_lshlrev_b32_e32 v5, 16, v231
	v_fmac_f32_e32 v3, v2, v5
	v_and_b32_e32 v5, 0xffff0000, v231
	v_fmac_f32_e32 v4, v2, v2
	v_and_b32_e32 v2, 0xffff0000, v127
	v_fmac_f32_e32 v4, v2, v2
	v_fmac_f32_e32 v3, v2, v5
	v_lshlrev_b32_e32 v2, 16, v128
	v_fmac_f32_e32 v4, v2, v2
	s_waitcnt vmcnt(0)
	v_lshlrev_b32_e32 v5, 16, v232
	v_fmac_f32_e32 v3, v2, v5
	v_and_b32_e32 v2, 0xffff0000, v128
	v_and_b32_e32 v5, 0xffff0000, v232
	v_fmac_f32_e32 v4, v2, v2
	v_fmac_f32_e32 v3, v2, v5
	v_lshlrev_b32_e32 v2, 16, v129
	v_lshlrev_b32_e32 v5, 16, v233
	v_fmac_f32_e32 v4, v2, v2
	v_fmac_f32_e32 v3, v2, v5
	v_and_b32_e32 v2, 0xffff0000, v129
	v_and_b32_e32 v5, 0xffff0000, v233
	v_fmac_f32_e32 v4, v2, v2
	v_fmac_f32_e32 v3, v2, v5
	v_lshlrev_b32_e32 v2, 16, v130
	v_lshlrev_b32_e32 v5, 16, v234
	v_fmac_f32_e32 v4, v2, v2
	v_fmac_f32_e32 v3, v2, v5
	v_and_b32_e32 v2, 0xffff0000, v130
	v_and_b32_e32 v5, 0xffff0000, v234
	v_fmac_f32_e32 v4, v2, v2
	v_fmac_f32_e32 v3, v2, v5
	v_lshlrev_b32_e32 v2, 16, v131
	v_lshlrev_b32_e32 v5, 16, v235
	v_fmac_f32_e32 v4, v2, v2
	v_fmac_f32_e32 v3, v2, v5
	v_and_b32_e32 v2, 0xffff0000, v131
	v_and_b32_e32 v5, 0xffff0000, v235
	v_fmac_f32_e32 v4, v2, v2
	v_fmac_f32_e32 v3, v2, v5
	v_xor_b32_e32 v5, 32, v186
	v_add_u32_e32 v2, 64, v197
	v_cmp_lt_i32_e32 vcc, v5, v2
	s_nop 1
	v_cndmask_b32_e32 v5, v186, v5, vcc
	v_lshlrev_b32_e32 v198, 2, v5
	ds_bpermute_b32 v5, v198, v4
	s_waitcnt lgkmcnt(0)
	v_add_f32_e32 v4, v4, v5
	ds_bpermute_b32 v5, v198, v3
	v_cmp_gt_f32_e32 vcc, s0, v4
	s_waitcnt lgkmcnt(0)
	v_add_f32_e32 v3, v3, v5
	v_mul_f32_e32 v5, 0x4f800000, v4
	v_cndmask_b32_e32 v4, v4, v5, vcc
	v_sqrt_f32_e32 v5, v4
	s_nop 0
	v_add_u32_e32 v6, -1, v5
	v_fma_f32 v7, -v6, v5, v4
	v_cmp_ge_f32_e64 s[0:1], 0, v7
	v_add_u32_e32 v7, 1, v5
	s_nop 0
	v_cndmask_b32_e64 v6, v5, v6, s[0:1]
	v_fma_f32 v5, -v7, v5, v4
	v_cmp_lt_f32_e64 s[0:1], 0, v5
	s_nop 1
	v_cndmask_b32_e64 v5, v6, v7, s[0:1]
	v_mul_f32_e32 v6, 0x37800000, v5
	v_cndmask_b32_e32 v5, v5, v6, vcc
	v_cmp_class_f32_e32 vcc, v4, v183
	v_lshl_add_u64 v[6:7], v[154:155], 2, s[4:5]
	s_nop 0
	v_cndmask_b32_e32 v4, v5, v4, vcc
	v_mov_b32_e32 v5, v236
	v_mul_f32_e32 v4, 0x3f800347, v4
	s_nop 0
	v_add_f32_e32 v5, v5, v0
	v_sub_f32_e32 v3, v5, v3
	v_xor_b32_e32 v5, 16, v186
	v_cmp_lt_i32_e32 vcc, v5, v2
	s_nop 1
	v_cndmask_b32_e32 v5, v186, v5, vcc
	v_lshlrev_b32_e32 v199, 2, v5
	ds_bpermute_b32 v5, v199, v4
	s_waitcnt lgkmcnt(0)
	v_max_f32_e32 v5, v5, v5
	v_max_f32_e32 v4, v4, v5
	ds_bpermute_b32 v5, v199, v3
	s_waitcnt lgkmcnt(0)
	v_max_f32_e32 v5, v5, v5
	v_max_f32_e32 v3, v3, v5
	v_xor_b32_e32 v5, 8, v186
	v_cmp_lt_i32_e32 vcc, v5, v2
	s_nop 1
	v_cndmask_b32_e32 v5, v186, v5, vcc
	v_lshlrev_b32_e32 v200, 2, v5
	ds_bpermute_b32 v5, v200, v4
	s_waitcnt lgkmcnt(0)
	v_max_f32_e32 v5, v5, v5
	v_max_f32_e32 v4, v4, v5
	ds_bpermute_b32 v5, v200, v3
	s_waitcnt lgkmcnt(0)
	v_max_f32_e32 v5, v5, v5
	v_max_f32_e32 v3, v3, v5
	v_xor_b32_e32 v5, 4, v186
	v_cmp_lt_i32_e32 vcc, v5, v2
	s_nop 1
	v_cndmask_b32_e32 v5, v186, v5, vcc
	v_lshlrev_b32_e32 v201, 2, v5
	ds_bpermute_b32 v5, v201, v4
	s_waitcnt lgkmcnt(0)
	v_max_f32_e32 v5, v5, v5
	v_max_f32_e32 v4, v4, v5
	ds_bpermute_b32 v5, v201, v3
	s_waitcnt lgkmcnt(0)
	v_max_f32_e32 v5, v5, v5
	v_max_f32_e32 v5, v3, v5
	v_xor_b32_e32 v3, 2, v186
	v_cmp_lt_i32_e32 vcc, v3, v2
	s_nop 1
	v_cndmask_b32_e32 v3, v186, v3, vcc
	v_lshlrev_b32_e32 v202, 2, v3
	ds_bpermute_b32 v3, v202, v4
	s_waitcnt lgkmcnt(0)
	v_max_f32_e32 v3, v3, v3
	v_max_f32_e32 v3, v4, v3
	ds_bpermute_b32 v4, v202, v5
	s_waitcnt lgkmcnt(0)
	v_max_f32_e32 v4, v4, v4
	v_max_f32_e32 v4, v5, v4
	v_xor_b32_e32 v5, 1, v186
	v_cmp_lt_i32_e32 vcc, v5, v2
	s_nop 1
	v_cndmask_b32_e32 v2, v186, v5, vcc
	v_lshlrev_b32_e32 v203, 2, v2
	ds_bpermute_b32 v2, v203, v3
	ds_bpermute_b32 v5, v203, v4
	s_and_saveexec_b64 s[0:1], s[6:7]
	s_cbranch_execz .LBB0_753
	s_waitcnt lgkmcnt(0)
	v_max_f32_e32 v5, v5, v5
	v_max_f32_e32 v4, v4, v4
	v_max_f32_e32 v2, v2, v2
	v_max_f32_e32 v3, v3, v3
	v_readlane_b32 s9, v254, 27
	v_max_f32_e32 v4, v4, v5
	v_max_f32_e32 v2, v3, v2
	v_mov_b32_e32 v3, s9
	ds_write2_b32 v3, v2, v4 offset1:8
